# mixer in-proj feature-major part: second-round units use feature tile pm^2 so the rotary(k_r) tile epilogues are spread over twice as many workgroups
# speedup vs baseline: 1.0105x; 1.0016x over previous
;     __host__ __device__ bool next(int i, Unit& u) const {
;         const long L = (long)i * G + c; if (L >= nwg) return false;
;         int wgid = (int)L; { const int q = nwg / NXCD, r = nwg % NXCD, xcd = wgid % NXCD, off = wgid / NXCD; wgid = (xcd < r ? xcd * (q + 1) : r * (q + 1) + (xcd - r) * q) + off; }
;         const int nig = WGM * nN, gid = wgid / nig, fm = gid * WGM, gsz = (nM - fm) < WGM ? (nM - fm) : WGM;
;         u.pm = fm + ((wgid % nig) % gsz); u.pn = (wgid % nig) / gsz; return true;
.LBB0_605:
	s_ashr_i32 s18, s20, 3
	s_add_i32 s18, s22, s18
	s_ashr_i32 s19, s18, 31
	s_lshr_b32 s19, s19, 22
	s_add_i32 s19, s18, s19
	s_ashr_i32 s20, s19, 10
	s_lshl_b32 s20, s20, 3
	s_sub_i32 s21, 4, s20
	s_min_i32 s21, s21, 8
	s_abs_i32 s22, s21
	v_cvt_f32_u32_e32 v0, s22
	s_sub_i32 s24, 0, s22
	s_and_b32 s19, s19, 0xfffffc00
	s_sub_i32 s19, s18, s19
	v_rcp_iflag_f32_e32 v0, v0
	s_abs_i32 s18, s19
	s_xor_b32 s23, s19, s21
	s_ashr_i32 s23, s23, 31
	v_mul_f32_e32 v0, 0x4f7ffffe, v0
	v_cvt_u32_f32_e32 v0, v0
	s_nop 0
	v_readfirstlane_b32 s25, v0
	s_mul_i32 s24, s24, s25
	s_mul_hi_u32 s24, s25, s24
	s_add_i32 s25, s25, s24
	s_mul_hi_u32 s24, s18, s25
	s_mul_i32 s25, s24, s22
	s_sub_i32 s18, s18, s25
	s_add_i32 s34, s24, 1
	s_sub_i32 s25, s18, s22
	s_cmp_ge_u32 s18, s22
	s_cselect_b32 s24, s34, s24
	s_cselect_b32 s18, s25, s18
	s_add_i32 s25, s24, 1
	s_cmp_ge_u32 s18, s22
	s_cselect_b32 s18, s25, s24
	s_xor_b32 s18, s18, s23
	s_sub_i32 s18, s18, s23
	s_mul_i32 s21, s18, s21
	s_sub_i32 s19, s19, s21
	s_add_i32 s20, s20, s19
	s_cmp_eq_u32 s94, 0x100
	s_cselect_b32 s19, 2, 0
	s_xor_b32 s20, s20, s19
